# poll-loop tightening: no s_sleep between granule polls in the P7 row-sum exchange; rest as v166
# speedup vs baseline: 1.0067x; 1.0067x over previous
;     __device__ __forceinline__ bool run(const f32x4 (&v)[2][2][4][2], const Unit& u, int wr, int wc, int fr, int fq, PG8_LAS unsigned char* lds, int wid, int lane) const {
;     ...
;         if (wid == 0) {
;             bool dead = false; const unsigned long long t0 = __builtin_amdgcn_s_memrealtime();
;             for (;;) {
;                 if ((unsigned)__builtin_amdgcn_readfirstlane(__hip_atomic_load(cnt + 64 * u.pm, __ATOMIC_RELAXED, __HIP_MEMORY_SCOPE_AGENT)) >= 64u) break;
;                 if (__builtin_amdgcn_s_memrealtime() - t0 > 2000000ull) { if (lane == 0) __hip_atomic_store(tmo, 1u, __ATOMIC_RELAXED, __HIP_MEMORY_SCOPE_AGENT); dead = true; break; }
;                 __builtin_amdgcn_s_sleep(2);
;             }
;             if (lane == 0) flag[0] = dead ? 1u : 0u;
;         }
;         asm volatile("s_waitcnt vmcnt(0) lgkmcnt(0)" ::: "memory"); __builtin_amdgcn_s_barrier(); asm volatile("" ::: "memory");
;         const bool bad = flag[0] != 0u;
;         if (lane < 32) { const unsigned* slot = xbuf + (size_t)(u.pm * BM + row) * 8; float s = 0.f;
; #pragma unroll
;             for (int t = 0; t < 8; ++t) s += __uint_as_float(__hip_atomic_load(slot + t, __ATOMIC_RELAXED, __HIP_MEMORY_SCOPE_AGENT));
;             S[row] = 1.0f / sqrtf(s * (1.0f / 2048.0f) + 1e-6f); }
.Lgx_poll:
	global_load_dwordx4 v[162:165], v159, s[44:45] sc1
	global_load_dwordx4 v[166:169], v159, s[44:45] offset:16 sc1
	global_load_dwordx4 v[170:173], v159, s[44:45] offset:32 sc1
	global_load_dwordx4 v[174:177], v159, s[44:45] offset:48 sc1
	s_waitcnt vmcnt(0)
	v_xor_b32_e32 v178, v163, v161
	v_xor_b32_e32 v179, v165, v161
	v_or_b32_e32 v178, v178, v179
	v_xor_b32_e32 v179, v167, v161
	v_or_b32_e32 v178, v178, v179
	v_xor_b32_e32 v179, v169, v161
	v_or_b32_e32 v178, v178, v179
	v_xor_b32_e32 v179, v171, v161
	v_or_b32_e32 v178, v178, v179
	v_xor_b32_e32 v179, v173, v161
	v_or_b32_e32 v178, v178, v179
	v_xor_b32_e32 v179, v175, v161
	v_or_b32_e32 v178, v178, v179
	v_xor_b32_e32 v179, v177, v161
	v_or_b32_e32 v178, v178, v179
	v_cmp_ne_u32_e32 vcc, 0, v178
	s_cbranch_vccz .Lgx_got
	s_sub_u32 s47, s47, 1
	s_cmp_lg_u32 s47, 0
	s_cbranch_scc1 .Lgx_poll
